# attention: the -rowmax blocks of the next tile are filled at the end of the iteration (after the LDS writes, before the barrier) instead of at its start
# speedup vs baseline: 1.0038x; 1.0038x over previous
.LBB0_346:
	s_mov_b64 s[98:99], s[88:89]
	s_mov_b64 s[100:101], s[88:89]
	v_sub_f32_e32 v176, 0, v233
	v_sub_f32_e32 v177, 0, v233
	v_sub_f32_e32 v178, 0, v233
	v_sub_f32_e32 v179, 0, v233
	v_sub_f32_e32 v180, 0, v233
	v_sub_f32_e32 v181, 0, v233
	v_sub_f32_e32 v182, 0, v233
	v_sub_f32_e32 v183, 0, v233
	v_sub_f32_e32 v184, 0, v233
	v_sub_f32_e32 v185, 0, v233
	v_sub_f32_e32 v186, 0, v233
	v_sub_f32_e32 v187, 0, v233
	v_sub_f32_e32 v188, 0, v233
	v_sub_f32_e32 v189, 0, v233
	v_sub_f32_e32 v190, 0, v233
	v_sub_f32_e32 v191, 0, v233
	v_sub_f32_e32 v80, 0, v234
	v_sub_f32_e32 v81, 0, v234
	v_sub_f32_e32 v82, 0, v234
	v_sub_f32_e32 v83, 0, v234
	v_sub_f32_e32 v84, 0, v234
	v_sub_f32_e32 v85, 0, v234
	v_sub_f32_e32 v86, 0, v234
	v_sub_f32_e32 v87, 0, v234
	v_sub_f32_e32 v88, 0, v234
	v_sub_f32_e32 v89, 0, v234
	v_sub_f32_e32 v90, 0, v234
	v_sub_f32_e32 v91, 0, v234
	v_sub_f32_e32 v92, 0, v234
	v_sub_f32_e32 v93, 0, v234
	v_sub_f32_e32 v94, 0, v234
	v_sub_f32_e32 v95, 0, v234
.Lat_loop:
	s_cmp_lg_u32 s1, 64
	s_cselect_b64 s[28:29], -1, 0
	s_and_b32 s4, 1, s1
	s_cselect_b32 s5, 0, 0x5800
	v_add3_u32 v235, s5, v223, v198
	v_add_u32_e32 v218, s5, v224
	ds_read_b128 v[236:239], v235
	ds_read_b128 v[240:243], v235 offset:6656
	ds_read_b128 v[244:247], v235 offset:32
	ds_read_b128 v[248:251], v235 offset:6688
	s_waitcnt lgkmcnt(3)
	v_mfma_f32_32x32x16_bf16 v[64:79], v[236:239], v[128:131], v[176:191]
	v_mfma_f32_32x32x16_bf16 v[96:111], v[236:239], v[152:155], v[80:95]
	ds_read_b128 v[236:239], v235 offset:64
	s_waitcnt lgkmcnt(3)
	v_mfma_f32_32x32x16_bf16 v[112:127], v[240:243], v[152:155], v[80:95]
	v_mfma_f32_32x32x16_bf16 v[80:95], v[240:243], v[128:131], v[176:191]
	ds_read_b128 v[240:243], v235 offset:6720
	s_waitcnt lgkmcnt(3)
	v_mfma_f32_32x32x16_bf16 v[64:79], v[244:247], v[132:135], v[64:79]
	v_mfma_f32_32x32x16_bf16 v[96:111], v[244:247], v[156:159], v[96:111]
	ds_read_b128 v[244:247], v235 offset:96
	s_waitcnt lgkmcnt(3)
	v_mfma_f32_32x32x16_bf16 v[80:95], v[248:251], v[132:135], v[80:95]
	v_mfma_f32_32x32x16_bf16 v[112:127], v[248:251], v[156:159], v[112:127]
	ds_read_b128 v[248:251], v235 offset:6752
	s_cmp_lg_u32 s1, 64
	s_cbranch_scc0 .Lat_skipld
	global_load_dwordx4 v[176:179], v208, s[98:99]
	global_load_dwordx4 v[180:183], v210, s[98:99]
	global_load_dwordx4 v[184:187], v212, s[98:99]
	global_load_dwordx4 v[188:191], v204, s[100:101]
	global_load_dwordx4 v[192:195], v206, s[100:101]

.Lat_nowr:
	s_add_i32 s1, s1, 1
	s_add_u32 s98, s98, s54
	s_addc_u32 s99, s99, s55
	s_add_u32 s100, s100, s76
	s_addc_u32 s101, s101, s77
	v_sub_f32_e32 v176, 0, v233
	v_sub_f32_e32 v177, 0, v233
	v_sub_f32_e32 v178, 0, v233
	v_sub_f32_e32 v179, 0, v233
	v_sub_f32_e32 v180, 0, v233
	v_sub_f32_e32 v181, 0, v233
	v_sub_f32_e32 v182, 0, v233
	v_sub_f32_e32 v183, 0, v233
	v_sub_f32_e32 v184, 0, v233
	v_sub_f32_e32 v185, 0, v233
	v_sub_f32_e32 v186, 0, v233
	v_sub_f32_e32 v187, 0, v233
	v_sub_f32_e32 v188, 0, v233
	v_sub_f32_e32 v189, 0, v233
	v_sub_f32_e32 v190, 0, v233
	v_sub_f32_e32 v191, 0, v233
	v_sub_f32_e32 v80, 0, v234
	v_sub_f32_e32 v81, 0, v234
	v_sub_f32_e32 v82, 0, v234
	v_sub_f32_e32 v83, 0, v234
	v_sub_f32_e32 v84, 0, v234
	v_sub_f32_e32 v85, 0, v234
	v_sub_f32_e32 v86, 0, v234
	v_sub_f32_e32 v87, 0, v234
	v_sub_f32_e32 v88, 0, v234
	v_sub_f32_e32 v89, 0, v234
	v_sub_f32_e32 v90, 0, v234
	v_sub_f32_e32 v91, 0, v234
	v_sub_f32_e32 v92, 0, v234
	v_sub_f32_e32 v93, 0, v234
	v_sub_f32_e32 v94, 0, v234
	v_sub_f32_e32 v95, 0, v234
	s_cmpk_eq_i32 s1, 0x41
	s_waitcnt lgkmcnt(0)
	s_barrier
	s_cbranch_scc0 .Lat_loop
	s_nop 7
	s_nop 7
	s_branch .LBB0_343
	.p2align 6
	s_nop 0
	s_nop 0
	s_nop 0
	s_nop 0
